# grid barrier after the MLP-down phase becomes a 4-workgroup barrier for layers 0-2; the next layer's first Q/K/V store waits on a global MLP-down-done counter
# speedup vs baseline: 1.0156x; 1.0071x over previous
; #define GAS __attribute__((address_space(1)))
; #define EPI_IDS() int t_ = threadIdx.x; asm volatile("" : "+v"(t_)); const int wid_ = __builtin_amdgcn_readfirstlane(t_ >> 6), wr = wid_ >> 2, wc = wid_ & 3, fr = t_ & 15, fq = (t_ & 63) >> 4;
;     __device__ __forceinline__ void operator()(const AccT& acc, const Unit& u, int, int, int, int) const {
;         EPI_IDS();
;         const int row0 = u.pm * BM + wr * 64 + fr;
;         const int pn = u.pn;
;         u64 sq[2][4];
; #pragma unroll
;         for (int ai = 0; ai < 2; ++ai)
; #pragma unroll
;             for (int m = 0; m < 4; ++m) sq[ai][m] = *(const GAS u64*)(ss + row0 + ai * HALF + m * 16);
.LBB0_196:
	s_cmp_lg_u32 s57, 1
	s_cbranch_scc1 .Lg6_skip
	v_mov_b32_e32 v130, 0x20008
	ds_read_b32 v130, v130
	s_waitcnt lgkmcnt(0)
	v_readfirstlane_b32 s4, v130
	s_nop 3
	s_cmp_lg_u32 s4, 1
	s_cbranch_scc1 .Lg6_skip
	v_cmp_eq_u32_e32 vcc, 0, v238
	s_and_saveexec_b64 s[2:3], vcc
	s_cbranch_execz .Lg6_join
	v_readlane_b32 s4, v253, 22
	s_nop 3
	s_mul_i32 s4, s4, 3
	s_add_i32 s4, s4, s44
	s_lshl_b32 s4, s4, 8
	v_mov_b32_e32 v206, s4
	v_readlane_b32 s4, v254, 30
	s_nop 3
	v_mov_b32_e32 v130, s4
	v_readlane_b32 s4, v254, 31
	s_nop 3
	v_mov_b32_e32 v131, s4
	v_add_co_u32_e32 v130, vcc, 0x30000c, v130
	s_nop 1
	v_addc_co_u32_e32 v131, vcc, 0, v131, vcc
	v_mov_b32_e32 v224, 0
.Lg6_spin:
	flat_load_dword v207, v[130:131] sc1
	s_waitcnt vmcnt(0) lgkmcnt(0)
	v_cmp_lt_u32_e32 vcc, v207, v206
	s_cbranch_vccz .Lg6_join
	s_sleep 1
	v_add_u32_e32 v224, 1, v224
	v_cmp_gt_u32_e32 vcc, 0x100000, v224
	s_cbranch_vccnz .Lg6_spin
.Lg6_join:
	s_or_b64 exec, exec, s[2:3]
	s_barrier

; __device__ __forceinline__ unsigned xb_ld(unsigned* p)              { return __hip_atomic_load(p, __ATOMIC_RELAXED, __HIP_MEMORY_SCOPE_AGENT); }
; __device__ __forceinline__ unsigned xb_add(unsigned* p, unsigned v) { return __hip_atomic_fetch_add(p, v, __ATOMIC_RELAXED, __HIP_MEMORY_SCOPE_AGENT); }
; #define XB_SPIN(cond, bar) do { unsigned _sp = 0; while (cond) { __builtin_amdgcn_s_sleep(1); \
;     if ((++_sp & 255u) == 0u) { if (xb_ld(&(bar)[XB_TMO])) break; if (_sp > XB_SPIN_CAP) { atomicAdd(&(bar)[XB_TMO], 1u); break; } } } } while (0)
; __device__ __forceinline__ void xcd_barrier(const XcdBarrier& b) {
;     asm volatile("s_waitcnt vmcnt(0)" ::: "memory");
;     __syncthreads();
;     if (threadIdx.x == 0) {
;         unsigned* bar = b.bar;
;         __builtin_amdgcn_s_waitcnt(0);
;         unsigned nloc = b.st[0], nx = b.st[1];
;         if (nloc == 0u) { xcd_barrier_complete(bar, b.x, nloc, nx); b.st[0] = nloc; b.st[1] = nx; }
;         const unsigned old = xb_add(&bar[XB_XSUB(b.x)], 1u);
;         const unsigned gen = old / nloc;
;         if (old + 1u == (gen + 1u) * nloc) {
;             __builtin_amdgcn_fence(__ATOMIC_RELEASE, "agent");
;             asm volatile("s_waitcnt vmcnt(0)" ::: "memory");
;             const unsigned og = xb_add(&bar[XB_TOP], 1u);
;             const unsigned tg = og / nx;
;             if (og + 1u == (tg + 1u) * nx) xb_add(&bar[XB_TOPGEN], 1u);
;             else XB_SPIN(xb_ld(&bar[XB_TOPGEN]) == tg, bar);
;             __builtin_amdgcn_fence(__ATOMIC_ACQUIRE, "agent");
;             xb_add(&bar[XB_XGEN(b.x)], 1u);
.LBB0_1014:
	v_readlane_b32 s0, v254, 16
	v_readlane_b32 s14, v254, 30
	v_readlane_b32 s15, v254, 31
	s_mov_b64 s[42:43], s[14:15]
	s_getreg_b32 s0, hwreg(HW_REG_XCC_ID, 0, 4)
	s_waitcnt vmcnt(0)
	v_readlane_b32 s1, v254, 17
	v_readlane_b32 s2, v254, 18
	v_readlane_b32 s3, v254, 19
	v_readlane_b32 s4, v254, 20
	v_readlane_b32 s5, v254, 21
	v_readlane_b32 s6, v254, 22
	v_readlane_b32 s7, v254, 23
	v_readlane_b32 s8, v254, 24
	v_readlane_b32 s9, v254, 25
	v_readlane_b32 s10, v254, 26
	v_readlane_b32 s11, v254, 27
	v_readlane_b32 s12, v254, 28
	v_readlane_b32 s13, v254, 29
	s_barrier
	s_mov_b64 s[34:35], exec
	v_readlane_b32 s2, v254, 32
	v_readlane_b32 s3, v254, 33
	s_and_b64 s[2:3], s[34:35], s[2:3]
	s_mov_b64 exec, s[2:3]
	s_cbranch_execz .LBB0_183
	s_waitcnt vmcnt(0) lgkmcnt(0)
	v_mov_b32_e32 v0, 0x20008
	ds_read_b32 v2, v0
	s_waitcnt lgkmcnt(0)
	v_readfirstlane_b32 s4, v2
	s_nop 3
	s_cmp_eq_u32 s44, 3
	s_cbranch_scc1 .Lxg_P6
	s_cmp_eq_u32 s4, 1
	s_cbranch_scc0 .Lxg_P6
	v_readlane_b32 s10, v254, 30
	v_readlane_b32 s11, v254, 31
	s_and_b32 s12, s33, 7
	s_lshr_b32 s13, s33, 3
	s_and_b32 s13, s13, 7
	s_lshl_b32 s12, s12, 3
	s_or_b32 s12, s12, s13
	s_and_b32 s13, s12, 15
	s_lshl_b32 s13, s13, 8
	s_lshr_b32 s12, s12, 4
	s_lshl_b32 s12, s12, 2
	s_add_u32 s12, s12, s13
	s_add_u32 s6, s10, 0x300010
	s_addc_u32 s7, s11, 0
	s_add_u32 s6, s6, s12
	s_addc_u32 s7, s7, 0
	s_add_u32 s12, s10, 0x30000c
	s_addc_u32 s13, s11, 0
	v_mov_b32_e32 v6, s12
	v_mov_b32_e32 v7, s13
	v_mov_b32_e32 v8, 1
	flat_atomic_add v[6:7], v8
	v_mov_b32_e32 v2, s6
	v_mov_b32_e32 v3, s7
	v_mov_b32_e32 v4, 1
	flat_atomic_add v4, v[2:3], v4 sc0
	s_mov_b32 s8, 0
	s_waitcnt vmcnt(0) lgkmcnt(0)
	v_and_b32_e32 v4, 0xfffffffc, v4
	v_add_u32_e32 v4, 4, v4

; __device__ __forceinline__ unsigned xb_ld(unsigned* p)              { return __hip_atomic_load(p, __ATOMIC_RELAXED, __HIP_MEMORY_SCOPE_AGENT); }
; __device__ __forceinline__ void xcd_barrier_complete(unsigned* bar, unsigned x, unsigned& nloc, unsigned& nx) {
;     const unsigned G = gridDim.x * gridDim.y * gridDim.z;
;     unsigned sum, cnt, mine, sp = 0u;
;     for (;;) {
;         sum = 0u; cnt = 0u; mine = 0u;
; #pragma unroll
;         for (unsigned j = 0; j < 16; ++j) { const unsigned c = xb_ld(&bar[XB_XCNT(j)]); sum += c; cnt += (c > 0u) ? 1u : 0u; mine = (j == x) ? c : mine; }
;         if (sum == G) break;
;         __builtin_amdgcn_s_sleep(1);
;         if ((++sp & 255u) == 0u) { if (xb_ld(&bar[XB_TMO])) break; if (sp > XB_SPIN_CAP) { atomicAdd(&bar[XB_TMO], 1u); break; } }
;     }
;     nloc = mine > 0u ? mine : 1u; nx = cnt > 0u ? cnt : 1u;
; }
; __device__ __forceinline__ void xcd_barrier(const XcdBarrier& b) {
;     asm volatile("s_waitcnt vmcnt(0)" ::: "memory");
;     __syncthreads();
;     if (threadIdx.x == 0) {
;         unsigned* bar = b.bar;
;         __builtin_amdgcn_s_waitcnt(0);
;         unsigned nloc = b.st[0], nx = b.st[1];
;         if (nloc == 0u) { xcd_barrier_complete(bar, b.x, nloc, nx); b.st[0] = nloc; b.st[1] = nx; }
.Lxg_P6:
	v_readlane_b32 s1, v253, 18
	s_waitcnt vmcnt(0) expcnt(0) lgkmcnt(0)
	s_and_b32 s0, s0, 15
	v_mov_b32_e32 v0, s1
	ds_read_b32 v2, v0
	v_readlane_b32 s1, v253, 19
	s_waitcnt lgkmcnt(0)
	v_cmp_ne_u32_e32 vcc, 0, v2
	v_mov_b32_e32 v0, s1
	ds_read_b32 v0, v0
	s_cbranch_vccnz .LBB0_1029
	s_add_u32 s2, s42, 0x300200
	s_addc_u32 s3, s43, 0
	s_add_u32 s4, s42, 0x300400
	s_addc_u32 s5, s43, 0
	s_add_u32 s6, s42, 0x300500
	s_addc_u32 s7, s43, 0
	s_add_u32 s8, s42, 0x300600
	s_addc_u32 s9, s43, 0
	s_add_u32 s10, s42, 0x300700
	s_addc_u32 s11, s43, 0
	s_add_u32 s12, s42, 0x300800
	s_addc_u32 s13, s43, 0
	s_add_u32 s14, s42, 0x300900
	s_addc_u32 s15, s43, 0
	s_add_u32 s16, s42, 0x300a00
	s_addc_u32 s17, s43, 0
	s_add_u32 s18, s42, 0x300b00
	s_addc_u32 s19, s43, 0
	s_add_u32 s20, s42, 0x300c00
	s_addc_u32 s21, s43, 0
	s_add_u32 s22, s42, 0x300d00
	s_addc_u32 s23, s43, 0
	s_add_u32 s24, s42, 0x300e00
	s_addc_u32 s25, s43, 0
	s_add_u32 s26, s42, 0x300f00
	s_addc_u32 s27, s43, 0
	s_add_u32 s28, s42, 0x301000
	s_addc_u32 s29, s43, 0
	s_add_u32 s30, s42, 0x301100
	s_addc_u32 s31, s43, 0
	s_add_u32 s56, s42, 0x301200
	s_addc_u32 s57, s43, 0
	s_add_u32 s72, s42, 0x301300
	s_addc_u32 s73, s43, 0
	s_mov_b32 s1, 1
	s_mov_b64 s[74:75], 0
	s_branch .LBB0_1019
